# adaLN modulation GEMV loop: rows two batches ahead are touched early by scratch loads (clamped to the thread's k range) so the real row loads stop exposing a full HBM round trip per batch
# speedup vs baseline: 1.0004x; 1.0004x over previous
.LBB0_106:
	v_mov_b32_e32 v31, v10
	v_mov_b64_e32 v[12:13], v[14:15]
	v_mad_i64_i32 v[14:15], s[34:35], v31, s29, v[6:7]
	global_load_dword v30, v[14:15], off
	v_add_u32_e32 v10, 1, v31
	v_mov_b32_e32 v22, v27
	v_add_u32_e32 v24, 2, v31
	v_add_u32_e32 v27, 3, v31
	v_add_u32_e32 v32, 4, v31
	v_add_u32_e32 v34, 5, v31
	v_add_u32_e32 v36, 6, v31
	v_add_u32_e32 v38, 7, v31
	v_mad_i64_i32 v[14:15], s[34:35], v10, s29, v[6:7]
	v_mov_b32_e32 v23, v28
	v_mad_i64_i32 v[24:25], s[34:35], v24, s29, v[6:7]
	v_mad_i64_i32 v[28:29], s[34:35], v27, s29, v[6:7]
	v_mad_i64_i32 v[32:33], s[34:35], v32, s29, v[6:7]
	v_mad_i64_i32 v[34:35], s[34:35], v34, s29, v[6:7]
	v_mad_i64_i32 v[36:37], s[34:35], v36, s29, v[6:7]
	v_mad_i64_i32 v[38:39], s[34:35], v38, s29, v[6:7]
	global_load_dword v40, v[14:15], off
	global_load_dword v42, v[24:25], off
	global_load_dword v44, v[28:29], off
	global_load_dword v46, v[32:33], off
	global_load_dword v48, v[34:35], off
	global_load_dword v50, v[36:37], off
	global_load_dword v52, v[38:39], off
	v_add_u32_e32 v90, 24, v31
	v_cmp_le_i32_e32 vcc, v90, v11
	v_mov_b32_e32 v91, 0x90000
	v_mov_b32_e32 v96, 0xffff7000
	v_cndmask_b32_e32 v90, 0, v91, vcc
	v_mov_b32_e32 v91, 0
	v_mov_b32_e32 v97, -1
	v_lshl_add_u64 v[92:93], v[14:15], 0, v[90:91]
	global_load_dword v98, v[92:93], off
	v_lshl_add_u64 v[94:95], v[92:93], 0, v[96:97]
	global_load_dword v105, v[94:95], off
	v_lshl_add_u64 v[92:93], v[24:25], 0, v[90:91]
	global_load_dword v99, v[92:93], off
	v_lshl_add_u64 v[92:93], v[28:29], 0, v[90:91]
	global_load_dword v100, v[92:93], off
	v_lshl_add_u64 v[92:93], v[32:33], 0, v[90:91]
	global_load_dword v101, v[92:93], off
	v_lshl_add_u64 v[92:93], v[34:35], 0, v[90:91]
	global_load_dword v102, v[92:93], off
	v_lshl_add_u64 v[92:93], v[36:37], 0, v[90:91]
	global_load_dword v103, v[92:93], off
	v_lshl_add_u64 v[92:93], v[38:39], 0, v[90:91]
	global_load_dword v104, v[92:93], off
	ds_read2_b32 v[32:33], v21 offset1:1
	ds_read2_b32 v[34:35], v21 offset0:2 offset1:3
	ds_read2_b32 v[36:37], v21 offset0:4 offset1:5
	ds_read2_b32 v[38:39], v21 offset0:6 offset1:7
	v_add_u32_e32 v10, 0x1000, v21
	v_mov_b32_e32 v24, v26
	v_add_u32_e32 v14, 0x2000, v21
	v_add_u32_e32 v15, 0x3000, v21
	v_add_u32_e32 v25, 0x1008, v21
	v_add_u32_e32 v26, 0x2008, v21
	v_add_u32_e32 v27, 0x3008, v21
	v_add_u32_e32 v28, 0x1010, v21
	v_add_u32_e32 v29, 0x2010, v21
	v_add_u32_e32 v41, 0x3010, v21
	v_add_u32_e32 v43, 0x1018, v21
	v_add_u32_e32 v45, 0x2018, v21
	v_add_u32_e32 v47, 0x3018, v21
	ds_read2_b32 v[54:55], v10 offset1:1
	ds_read2_b32 v[56:57], v25 offset1:1
	ds_read2_b32 v[58:59], v14 offset1:1
	ds_read2_b32 v[60:61], v15 offset1:1
	ds_read2_b32 v[62:63], v28 offset1:1
	ds_read2_b32 v[64:65], v26 offset1:1
	ds_read2_b32 v[66:67], v29 offset1:1
	ds_read2_b32 v[68:69], v27 offset1:1
	ds_read2_b32 v[70:71], v43 offset1:1
	ds_read2_b32 v[72:73], v45 offset1:1
	ds_read2_b32 v[74:75], v47 offset1:1
	ds_read2_b32 v[76:77], v41 offset1:1
	s_waitcnt lgkmcnt(14)
	v_mov_b32_e32 v78, v32
	s_waitcnt lgkmcnt(11)
	v_mov_b32_e32 v79, v54
	s_waitcnt lgkmcnt(9)
	v_mov_b32_e32 v80, v58
	s_waitcnt lgkmcnt(8)
	v_mov_b32_e32 v81, v60
	v_mov_b32_e32 v54, v33
	v_mov_b32_e32 v60, v59
	v_mov_b32_e32 v32, v34
	v_mov_b32_e32 v34, v36
	v_mov_b32_e32 v36, v38
	v_mov_b32_e32 v33, v56
	v_mov_b32_e32 v56, v35
	s_waitcnt lgkmcnt(7)
	v_mov_b32_e32 v35, v62
	v_mov_b32_e32 v62, v37
	s_waitcnt lgkmcnt(3)
	v_mov_b32_e32 v37, v70
	v_mov_b32_e32 v70, v39
	v_mov_b32_e32 v38, v64
	v_mov_b32_e32 v39, v68
	v_mov_b32_e32 v68, v65
	v_mov_b32_e32 v58, v66
	s_waitcnt lgkmcnt(0)
	v_mov_b32_e32 v59, v76
	v_mov_b32_e32 v76, v67
	v_add_u32_e32 v29, 16, v31
	v_mov_b32_e32 v64, v72
	v_mov_b32_e32 v65, v74
	s_add_i32 s16, s16, 1
	v_cmp_gt_i32_e32 vcc, v29, v11
	v_mov_b32_e32 v74, v73
	v_add_u32_e32 v21, 32, v21
	v_add_u32_e32 v10, 8, v31
	v_lshl_add_u64 v[14:15], v[12:13], 0, s[6:7]
	v_add_u32_e32 v27, 8, v22
	v_add_u32_e32 v28, 32, v23
	v_add_u32_e32 v26, 8, v24
	v_mov_b32_e32 v25, s16
	s_or_b64 s[14:15], vcc, s[14:15]
	s_waitcnt vmcnt(15)
	v_pk_fma_f32 v[0:1], v[30:31], v[78:79], v[0:1] op_sel_hi:[0,1,1]
	v_pk_fma_f32 v[2:3], v[30:31], v[80:81], v[2:3] op_sel_hi:[0,1,1]
	s_waitcnt vmcnt(14)
	v_pk_fma_f32 v[0:1], v[40:41], v[54:55], v[0:1] op_sel_hi:[0,1,1]
	v_pk_fma_f32 v[2:3], v[40:41], v[60:61], v[2:3] op_sel_hi:[0,1,1]
	s_waitcnt vmcnt(13)
	v_pk_fma_f32 v[0:1], v[42:43], v[32:33], v[0:1] op_sel_hi:[0,1,1]
	v_pk_fma_f32 v[2:3], v[42:43], v[38:39], v[2:3] op_sel_hi:[0,1,1]
	s_waitcnt vmcnt(12)
	v_pk_fma_f32 v[0:1], v[44:45], v[56:57], v[0:1] op_sel_hi:[0,1,1]
	v_pk_fma_f32 v[2:3], v[44:45], v[68:69], v[2:3] op_sel_hi:[0,1,1]
	s_waitcnt vmcnt(11)
	v_pk_fma_f32 v[0:1], v[46:47], v[34:35], v[0:1] op_sel_hi:[0,1,1]
	v_pk_fma_f32 v[2:3], v[46:47], v[58:59], v[2:3] op_sel_hi:[0,1,1]
	s_waitcnt vmcnt(10)
	v_pk_fma_f32 v[0:1], v[48:49], v[62:63], v[0:1] op_sel_hi:[0,1,1]
	v_pk_fma_f32 v[2:3], v[48:49], v[76:77], v[2:3] op_sel_hi:[0,1,1]
	s_waitcnt vmcnt(9)
	v_pk_fma_f32 v[0:1], v[50:51], v[36:37], v[0:1] op_sel_hi:[0,1,1]
	v_pk_fma_f32 v[2:3], v[50:51], v[64:65], v[2:3] op_sel_hi:[0,1,1]
	s_waitcnt vmcnt(8)
	v_pk_fma_f32 v[0:1], v[52:53], v[70:71], v[0:1] op_sel_hi:[0,1,1]
	v_pk_fma_f32 v[2:3], v[52:53], v[74:75], v[2:3] op_sel_hi:[0,1,1]
	s_andn2_b64 exec, exec, s[14:15]
	s_cbranch_execnz .LBB0_106
	s_or_b64 exec, exec, s[14:15]
	v_cmp_lt_i32_e32 vcc, v10, v11
	s_and_saveexec_b64 s[14:15], vcc
	s_cbranch_execz .LBB0_115
	v_and_b32_e32 v14, 3, v20
	v_lshlrev_b32_e32 v15, 2, v14
	s_mov_b32 s34, 0
	s_mov_b64 s[16:17], 0
